# attention phase: one static s_setprio 1 for waves 4-7 (younger half) at phase entry, reset at exit; on top of the up-GEMM load-segment recipe
# baseline (speedup 1.0000x reference)
; __device__ __forceinline__ int lane_id() { int l; asm volatile("v_mbcnt_lo_u32_b32 %0, -1, 0\n\tv_mbcnt_hi_u32_b32 %0, -1, %0" : "=v"(l)); return l; }
; #define VMW() asm volatile("s_waitcnt vmcnt(0)" ::: "memory")
; #define SLOAD_H(Kp, Vp, Bp, k0) do { S.st_v0 = load8(GROW(Vp, k0, voffk0)); S.st_v1 = load8(GROW(Vp, k0, voffk1));              \
;                          S.st_k0 = load8(GROW(Kp, k0, voffk0)); S.st_k1 = load8(GROW(Kp, k0, voffk1)); } while (0)
; #define SWRITE_HK(bf) do { *(bf16x8*)(K_lds + (bf) * SHM_K + kws) = S.st_k0; *(bf16x8*)(K_lds + (bf) * SHM_K + kws + 32 * 256) = S.st_k1; } while (0)
; __device__ __forceinline__ void fox_prime(const BlockRef& cur, char* lds, Seam& S, int wid) {
;     asm volatile("" : "+s"(wid));
;     int lane = lane_id(); asm volatile("" : "+v"(lane));
;     const int tid = wid * 64 + lane, r32 = lane & 31, hi = lane >> 5;
;     const int sr = tid >> 4, sc = (tid & 15) * 8, kws = KSWZ(sr, sc * 2); char* K_lds = lds + 2 * SHM_V;
;     const unsigned voffk0 = (unsigned)(sr * LDQ + sc) * 2u, voffk1 = voffk0 + 32u * LDQ * 2u, voffq = (unsigned)(r32 * LDQ + hi * 8) * 2u;
;     for (int d0 = 0; d0 < 8; ++d0) S.qr[d0] = load8((const bf16*)((const char*)(cur.Q + (size_t)(wid * QBLK) * LDQ) + voffq) + d0 * 16);
;     SLOAD_H(cur.K, cur.V, cur.Bias, ((cur.P0 + QB - 1) / KVBLK) * KVBLK); VMW(); SWRITE_HK(0);
;     __syncthreads();
; }
; __global__ void __launch_bounds__(NWAVES * 64, 2) mega_fwd(Args args) {
;     ...
;                 if (bx < total) {
;                     auto mkref = [&](int L, int pass) { const int bh = L >> 2, xq = L & 3; const int qb = pass ? 7 - xq : xq; const int bp = bh >> 4, h = bh & 15; const int b = bp < 8 ? 2 * bp + 1 : 2 * (bp - 8);
;                         fox::BlockRef r; const size_t rowb = (size_t)b * SEQ;
;                         r.Q = (const fox::bf16*)QKV + (rowb + qb * 256) * QKV_LD + h * HD; r.K = (const fox::bf16*)QKV + rowb * QKV_LD + DM + h * HD; r.V = (const fox::bf16*)QKV + rowb * QKV_LD + 2 * DM + h * HD;
;                         r.Bias = CB + (size_t)(b * 16 + h) * SEQ; r.O = (fox::bf16*)ATT + (rowb + qb * 256) * DM + h * HD; r.P0 = qb * 256; return r; };
;                     int L = bx, pass = 0; fox::BlockRef cur = mkref(L, 0); fox::Seam S;
;                     fox::fox_prime(cur, (char*)lds, S, wave_s);
.LBB0_643:
	s_mov_b64 s[8:9], s[0:1]
	s_mov_b64 s[4:5], s[0:1]
	s_waitcnt lgkmcnt(0)
	s_barrier
	s_mov_b64 s[4:5], s[0:1]
	s_nop 0
	v_readlane_b32 s4, v254, 0
	v_readlane_b32 s5, v254, 1
	s_and_b64 vcc, exec, s[4:5]
	s_cbranch_vccz .LBB0_814
	s_cmp_lt_u32 s33, 4
	s_cbranch_scc1 .Latt_prio_done
	s_setprio 1
.Latt_prio_done:
	s_load_dwordx2 s[4:5], s[8:9], 0xa0
	v_readlane_b32 s6, v254, 47
	s_mov_b32 s52, 0
	v_readlane_b32 s51, v254, 17
	s_mov_b32 s53, s2
	s_waitcnt lgkmcnt(0)
	s_add_u32 s36, s4, 0x13c00000
	s_addc_u32 s42, s5, 0
	s_add_u32 s43, s4, 0x2bc00000
	s_addc_u32 s48, s5, 0
	s_add_u32 s49, s4, 0x33e00000
	s_addc_u32 s50, s5, 0
	v_readlane_b32 s4, v254, 10
	s_add_u32 s4, s36, s4
	v_readlane_b32 s5, v254, 9
	s_addc_u32 s5, s42, s5
	s_add_u32 s12, s4, s6
	s_addc_u32 s13, s5, 0
	v_readlane_b32 s4, v254, 12
	s_add_u32 s4, s36, s4
	v_readlane_b32 s5, v254, 11
	s_addc_u32 s5, s42, s5
	s_add_u32 s4, s4, s6
	s_addc_u32 s5, s5, 0
	s_add_u32 s14, s4, 0x1000
	s_addc_u32 s15, s5, 0
	s_add_u32 s16, s4, 0x2000
	s_addc_u32 s17, s5, 0
	v_readlane_b32 s4, v254, 13
	v_readlane_b32 s5, v254, 14
	s_add_u32 s30, s49, s4
	s_addc_u32 s31, s50, s5
	v_readlane_b32 s4, v254, 15
	v_readlane_b32 s5, v254, 16
	s_add_u32 s4, s43, s4
	s_addc_u32 s5, s48, s5
	s_add_u32 s28, s4, s6
	s_mov_b32 s6, s33
	v_mbcnt_lo_u32_b32 v0, -1, 0
	v_mbcnt_hi_u32_b32 v0, -1, v0
	s_addc_u32 s29, s5, 0
	s_lshl_b32 s4, s6, 5
	v_and_b32_e32 v1, 31, v0
	v_ashrrev_i32_e32 v2, 2, v0
	s_mul_i32 s5, s6, 0x60000
	v_mul_u32_u24_e32 v1, 0x1800, v1
	v_and_b32_e32 v2, 0x7ffffff8, v2
	s_mul_hi_i32 s7, s4, 0x3000
	s_add_u32 s4, s12, s5
	v_add_lshl_u32 v1, v1, v2, 1
	s_addc_u32 s5, s13, s7
	global_load_dwordx4 v[156:159], v1, s[4:5]
	global_load_dwordx4 v[152:155], v1, s[4:5] offset:32
	global_load_dwordx4 v[148:151], v1, s[4:5] offset:64
	global_load_dwordx4 v[144:147], v1, s[4:5] offset:96
	global_load_dwordx4 v[140:143], v1, s[4:5] offset:128
	global_load_dwordx4 v[136:139], v1, s[4:5] offset:160
	global_load_dwordx4 v[132:135], v1, s[4:5] offset:192
	global_load_dwordx4 v[128:131], v1, s[4:5] offset:224
	v_lshl_add_u32 v1, s6, 6, v0
	v_ashrrev_i32_e32 v2, 4, v1
	v_lshlrev_b32_e32 v0, 3, v0
	v_mul_lo_u32 v3, v2, s87
	v_and_b32_e32 v0, 0x78, v0
	v_or_b32_e32 v3, v3, v0
	v_lshlrev_b32_e32 v0, 1, v0
	s_movk_i32 s4, 0x70
	v_readlane_b32 s6, v254, 18
	v_bitop3_b32 v9, v0, v1, s4 bitop3:0x78
	s_add_u32 s4, s16, s6
	v_lshlrev_b32_e32 v3, 1, v3
	s_addc_u32 s5, s17, 0
	v_add_u32_e32 v4, 0x60000, v3
	global_load_dwordx4 v[96:99], v3, s[4:5]
	global_load_dwordx4 v[100:103], v4, s[4:5]
	s_add_u32 s4, s14, s6
	s_addc_u32 s5, s15, 0
	v_lshlrev_b32_e32 v8, 8, v2
	global_load_dwordx4 v[0:3], v3, s[4:5]
	s_nop 0
	global_load_dwordx4 v[4:7], v4, s[4:5]
	s_waitcnt vmcnt(0)
	v_add3_u32 v8, 0, v8, v9
	s_waitcnt vmcnt(1)
	ds_write_b128 v8, v[0:3] offset:32768
	s_waitcnt vmcnt(0)
	ds_write_b128 v8, v[4:7] offset:40960
	s_waitcnt lgkmcnt(0)
	s_barrier
	s_branch .LBB0_646

; #define GBAR() grid_bar((unsigned*)karg_f(20), (volatile LAS unsigned*)((LAS unsigned char*)lds + LDS_BYTES - 64), wave_s)
; __global__ void __launch_bounds__(NWAVES * 64, 2) mega_fwd(Args args) {
;     ...
;                     }
;                 }
;             }
;             }
;             GBAR();
.LBB0_813:
	s_setprio 0
	v_readlane_b32 s92, v254, 48
	v_readlane_b32 s82, v254, 50
	v_readlane_b32 s52, v254, 52
	v_readlane_b32 s93, v254, 49
	v_readlane_b32 s83, v254, 51
	v_readlane_b32 s53, v254, 53
